# P7 panel exchange: dropped the L2 write-back / L1 invalidate around the 4-workgroup counter (only drained device-scope atomics are exchanged, read back with sc1 loads)
# speedup vs baseline: 1.2950x; 1.0039x over previous
.LBB0_1199:
	s_or_b64 exec, exec, s[8:9]
	s_waitcnt vmcnt(0)
	s_barrier
	s_and_saveexec_b64 s[8:9], s[4:5]
	s_cbranch_execz .LBB0_1211
	s_lshl_b32 s26, s38, 4
	s_mov_b64 s[36:37], exec
	s_ashr_i32 s27, s26, 31
	s_waitcnt vmcnt(0) lgkmcnt(0)
	s_waitcnt vmcnt(0)
	s_lshl_b64 s[26:27], s[26:27], 2
	v_mbcnt_lo_u32_b32 v0, s36, 0
	s_add_u32 s26, s43, s26
	v_mbcnt_hi_u32_b32 v0, s37, v0
	s_addc_u32 s27, s44, s27
	v_cmp_eq_u32_e32 vcc, 0, v0
	s_and_saveexec_b64 s[38:39], vcc
	s_cbranch_execz .LBB0_1202
	s_bcnt1_i32_b64 s36, s[36:37]
	v_mov_b32_e32 v0, s36
	global_atomic_add v129, v0, s[26:27]

.LBB0_1204:
	global_load_dword v0, v129, s[26:27] sc1
	s_mov_b64 s[36:37], -1
	s_waitcnt vmcnt(0)
	v_cmp_lt_u32_e32 vcc, 3, v0
	s_cbranch_vccnz .LBB0_1203
	s_sleep 1
	global_load_dword v0, v129, s[26:27] sc1
	s_waitcnt vmcnt(0)
	v_cmp_gt_u32_e32 vcc, 4, v0
	s_cbranch_vccz .LBB0_1203
	s_sleep 1
	global_load_dword v0, v129, s[26:27] sc1
	s_waitcnt vmcnt(0)
	v_cmp_gt_u32_e32 vcc, 4, v0
	s_cbranch_vccz .LBB0_1203
	s_sleep 1
	global_load_dword v0, v129, s[26:27] sc1
	s_waitcnt vmcnt(0)
	v_cmp_gt_u32_e32 vcc, 4, v0
	s_cbranch_vccz .LBB0_1203
	s_sleep 1
	global_load_dword v0, v129, s[26:27] sc1
	s_waitcnt vmcnt(0)
	v_cmp_gt_u32_e32 vcc, 4, v0
	s_cbranch_vccz .LBB0_1203
	s_add_i32 s38, s38, -5
	s_cmp_eq_u32 s38, 0
	s_cselect_b64 s[36:37], -1, 0
	s_sleep 1
	s_branch .LBB0_1203
.LBB0_1210:
	s_waitcnt vmcnt(0)
.LBB0_1211:
	s_or_b64 exec, exec, s[8:9]
	v_lshlrev_b64 v[140:141], 2, v[140:141]
	s_barrier
	s_waitcnt lgkmcnt(0)
	v_lshl_add_u64 v[0:1], s[28:29], 0, v[140:141]
	global_load_dwordx4 v[12:15], v[0:1], off
	global_load_dwordx4 v[8:11], v[0:1], off offset:64
	global_load_dwordx4 v[4:7], v[0:1], off offset:512
	s_nop 0
	global_load_dwordx4 v[0:3], v[0:1], off offset:576
	s_nop 0
	global_load_dword v150, v[150:151], off sc1
	v_lshlrev_b64 v[190:191], 10, v[148:149]
	v_lshlrev_b64 v[148:149], 10, v[182:183]
	v_lshlrev_b64 v[196:197], 10, v[142:143]
	v_lshlrev_b64 v[194:195], 10, v[144:145]
	v_lshlrev_b64 v[192:193], 10, v[146:147]
	v_lshlrev_b64 v[146:147], 10, v[184:185]
	v_lshlrev_b64 v[144:145], 10, v[186:187]
	v_lshlrev_b64 v[142:143], 10, v[188:189]
	s_waitcnt vmcnt(0)
	v_fmamk_f32 v150, v150, 0x3a800000, v205
	v_mul_f32_e32 v151, 0x4b800000, v150
	v_cmp_gt_f32_e32 vcc, s52, v150
	s_nop 1
	v_cndmask_b32_e32 v150, v150, v151, vcc
	v_rsq_f32_e32 v182, v150
	v_lshl_add_u64 v[150:151], v[196:197], 2, s[30:31]
	v_lshl_add_u64 v[150:151], v[150:151], 0, v[140:141]
	v_mul_f32_e32 v183, 0x45800000, v182
	v_cndmask_b32_e32 v182, v182, v183, vcc
	v_pk_mul_f32 v[124:125], v[124:125], v[182:183] op_sel_hi:[1,0]
	v_pk_mul_f32 v[126:127], v[126:127], v[182:183] op_sel_hi:[1,0]
	v_pk_mul_f32 v[120:121], v[120:121], v[182:183] op_sel_hi:[1,0]
	v_pk_mul_f32 v[122:123], v[122:123], v[182:183] op_sel_hi:[1,0]
	v_pk_mul_f32 v[184:185], v[116:117], v[182:183] op_sel_hi:[1,0]
	v_pk_mul_f32 v[186:187], v[118:119], v[182:183] op_sel_hi:[1,0]
	v_pk_mul_f32 v[188:189], v[112:113], v[182:183] op_sel_hi:[1,0]
	v_pk_mul_f32 v[182:183], v[114:115], v[182:183] op_sel_hi:[1,0]
	v_pk_mul_f32 v[114:115], v[14:15], v[126:127]
	v_pk_mul_f32 v[112:113], v[12:13], v[124:125]
	v_pk_mul_f32 v[118:119], v[10:11], v[122:123]
	v_pk_mul_f32 v[116:117], v[8:9], v[120:121]
	v_pk_mul_f32 v[122:123], v[6:7], v[186:187]
	v_pk_mul_f32 v[120:121], v[4:5], v[184:185]
	v_pk_mul_f32 v[126:127], v[2:3], v[182:183]
	v_pk_mul_f32 v[124:125], v[0:1], v[188:189]
	global_store_dwordx4 v[150:151], v[112:115], off
	global_store_dwordx4 v[150:151], v[116:119], off offset:64
	global_store_dwordx4 v[150:151], v[120:123], off offset:512
	global_store_dwordx4 v[150:151], v[124:127], off offset:576
	global_load_dword v112, v[152:153], off sc1
	s_waitcnt vmcnt(0)
	v_fmamk_f32 v112, v112, 0x3a800000, v205
	v_mul_f32_e32 v113, 0x4b800000, v112
	v_cmp_gt_f32_e32 vcc, s52, v112
	s_nop 1
	v_cndmask_b32_e32 v112, v112, v113, vcc
	v_rsq_f32_e32 v114, v112
	v_lshl_add_u64 v[112:113], v[194:195], 2, s[30:31]
	v_lshl_add_u64 v[112:113], v[112:113], 0, v[140:141]
	v_mul_f32_e32 v115, 0x45800000, v114
	v_cndmask_b32_e32 v114, v114, v115, vcc
	v_pk_mul_f32 v[108:109], v[108:109], v[114:115] op_sel_hi:[1,0]
	v_pk_mul_f32 v[110:111], v[110:111], v[114:115] op_sel_hi:[1,0]
	v_pk_mul_f32 v[104:105], v[104:105], v[114:115] op_sel_hi:[1,0]
	v_pk_mul_f32 v[106:107], v[106:107], v[114:115] op_sel_hi:[1,0]
	v_pk_mul_f32 v[116:117], v[100:101], v[114:115] op_sel_hi:[1,0]
	v_pk_mul_f32 v[118:119], v[102:103], v[114:115] op_sel_hi:[1,0]
	v_pk_mul_f32 v[120:121], v[96:97], v[114:115] op_sel_hi:[1,0]
	v_pk_mul_f32 v[114:115], v[98:99], v[114:115] op_sel_hi:[1,0]
	v_pk_mul_f32 v[98:99], v[14:15], v[110:111]
	v_pk_mul_f32 v[96:97], v[12:13], v[108:109]
	v_pk_mul_f32 v[102:103], v[10:11], v[106:107]
	v_pk_mul_f32 v[100:101], v[8:9], v[104:105]
	v_pk_mul_f32 v[106:107], v[6:7], v[118:119]
	v_pk_mul_f32 v[104:105], v[4:5], v[116:117]
	v_pk_mul_f32 v[110:111], v[2:3], v[114:115]
	v_pk_mul_f32 v[108:109], v[0:1], v[120:121]
	global_store_dwordx4 v[112:113], v[96:99], off
	global_store_dwordx4 v[112:113], v[100:103], off offset:64
	global_store_dwordx4 v[112:113], v[104:107], off offset:512
	global_store_dwordx4 v[112:113], v[108:111], off offset:576
	global_load_dword v96, v[154:155], off sc1
	s_waitcnt vmcnt(0)
	v_fmamk_f32 v96, v96, 0x3a800000, v205
	v_mul_f32_e32 v97, 0x4b800000, v96
	v_cmp_gt_f32_e32 vcc, s52, v96
	s_nop 1
	v_cndmask_b32_e32 v96, v96, v97, vcc
	v_rsq_f32_e32 v98, v96
	v_lshl_add_u64 v[96:97], v[192:193], 2, s[30:31]
	v_lshl_add_u64 v[96:97], v[96:97], 0, v[140:141]
	v_mul_f32_e32 v99, 0x45800000, v98
	v_cndmask_b32_e32 v98, v98, v99, vcc
	v_pk_mul_f32 v[92:93], v[92:93], v[98:99] op_sel_hi:[1,0]
	v_pk_mul_f32 v[94:95], v[94:95], v[98:99] op_sel_hi:[1,0]
	v_pk_mul_f32 v[88:89], v[88:89], v[98:99] op_sel_hi:[1,0]
	v_pk_mul_f32 v[90:91], v[90:91], v[98:99] op_sel_hi:[1,0]
	v_pk_mul_f32 v[100:101], v[84:85], v[98:99] op_sel_hi:[1,0]
	v_pk_mul_f32 v[102:103], v[86:87], v[98:99] op_sel_hi:[1,0]
	v_pk_mul_f32 v[104:105], v[80:81], v[98:99] op_sel_hi:[1,0]
	v_pk_mul_f32 v[98:99], v[82:83], v[98:99] op_sel_hi:[1,0]
	v_pk_mul_f32 v[82:83], v[14:15], v[94:95]
	v_pk_mul_f32 v[80:81], v[12:13], v[92:93]
	v_pk_mul_f32 v[86:87], v[10:11], v[90:91]
	v_pk_mul_f32 v[84:85], v[8:9], v[88:89]
	v_pk_mul_f32 v[90:91], v[6:7], v[102:103]
	v_pk_mul_f32 v[88:89], v[4:5], v[100:101]
	v_pk_mul_f32 v[94:95], v[2:3], v[98:99]
	v_pk_mul_f32 v[92:93], v[0:1], v[104:105]
	global_store_dwordx4 v[96:97], v[80:83], off
	global_store_dwordx4 v[96:97], v[84:87], off offset:64
	global_store_dwordx4 v[96:97], v[88:91], off offset:512
	global_store_dwordx4 v[96:97], v[92:95], off offset:576
	global_load_dword v80, v[156:157], off sc1
	s_waitcnt vmcnt(0)
	v_fmamk_f32 v80, v80, 0x3a800000, v205
	v_mul_f32_e32 v81, 0x4b800000, v80
	v_cmp_gt_f32_e32 vcc, s52, v80
	s_nop 1
	v_cndmask_b32_e32 v80, v80, v81, vcc
	v_rsq_f32_e32 v82, v80
	v_lshl_add_u64 v[80:81], v[190:191], 2, s[30:31]
	v_lshl_add_u64 v[80:81], v[80:81], 0, v[140:141]
	v_mul_f32_e32 v83, 0x45800000, v82
	v_cndmask_b32_e32 v82, v82, v83, vcc
	v_pk_mul_f32 v[76:77], v[76:77], v[82:83] op_sel_hi:[1,0]
	v_pk_mul_f32 v[78:79], v[78:79], v[82:83] op_sel_hi:[1,0]
	v_pk_mul_f32 v[72:73], v[72:73], v[82:83] op_sel_hi:[1,0]
	v_pk_mul_f32 v[74:75], v[74:75], v[82:83] op_sel_hi:[1,0]
	v_pk_mul_f32 v[84:85], v[68:69], v[82:83] op_sel_hi:[1,0]
	v_pk_mul_f32 v[86:87], v[70:71], v[82:83] op_sel_hi:[1,0]
	v_pk_mul_f32 v[88:89], v[64:65], v[82:83] op_sel_hi:[1,0]
	v_pk_mul_f32 v[82:83], v[66:67], v[82:83] op_sel_hi:[1,0]
	v_pk_mul_f32 v[66:67], v[14:15], v[78:79]
	v_pk_mul_f32 v[64:65], v[12:13], v[76:77]
	v_pk_mul_f32 v[70:71], v[10:11], v[74:75]
	v_pk_mul_f32 v[68:69], v[8:9], v[72:73]
	v_pk_mul_f32 v[74:75], v[6:7], v[86:87]
	v_pk_mul_f32 v[72:73], v[4:5], v[84:85]
	v_pk_mul_f32 v[78:79], v[2:3], v[82:83]
	v_pk_mul_f32 v[76:77], v[0:1], v[88:89]
	global_store_dwordx4 v[80:81], v[64:67], off
	global_store_dwordx4 v[80:81], v[68:71], off offset:64
	global_store_dwordx4 v[80:81], v[72:75], off offset:512
	global_store_dwordx4 v[80:81], v[76:79], off offset:576
	global_load_dword v64, v[174:175], off sc1
	s_waitcnt vmcnt(0)
	v_fmamk_f32 v64, v64, 0x3a800000, v205
	v_mul_f32_e32 v65, 0x4b800000, v64
	v_cmp_gt_f32_e32 vcc, s52, v64
	s_nop 1
	v_cndmask_b32_e32 v64, v64, v65, vcc
	v_rsq_f32_e32 v66, v64
	v_lshl_add_u64 v[64:65], v[148:149], 2, s[30:31]
	v_lshl_add_u64 v[64:65], v[64:65], 0, v[140:141]
	v_mul_f32_e32 v67, 0x45800000, v66
	v_cndmask_b32_e32 v66, v66, v67, vcc
	v_pk_mul_f32 v[60:61], v[60:61], v[66:67] op_sel_hi:[1,0]
	v_pk_mul_f32 v[62:63], v[62:63], v[66:67] op_sel_hi:[1,0]
	v_pk_mul_f32 v[56:57], v[56:57], v[66:67] op_sel_hi:[1,0]
	v_pk_mul_f32 v[58:59], v[58:59], v[66:67] op_sel_hi:[1,0]
	v_pk_mul_f32 v[68:69], v[52:53], v[66:67] op_sel_hi:[1,0]
	v_pk_mul_f32 v[70:71], v[54:55], v[66:67] op_sel_hi:[1,0]
	v_pk_mul_f32 v[72:73], v[48:49], v[66:67] op_sel_hi:[1,0]
	v_pk_mul_f32 v[66:67], v[50:51], v[66:67] op_sel_hi:[1,0]
	v_pk_mul_f32 v[50:51], v[14:15], v[62:63]
	v_pk_mul_f32 v[48:49], v[12:13], v[60:61]
	v_pk_mul_f32 v[54:55], v[10:11], v[58:59]
	v_pk_mul_f32 v[52:53], v[8:9], v[56:57]
	v_pk_mul_f32 v[58:59], v[6:7], v[70:71]
	v_pk_mul_f32 v[56:57], v[4:5], v[68:69]
	v_pk_mul_f32 v[62:63], v[2:3], v[66:67]
	v_pk_mul_f32 v[60:61], v[0:1], v[72:73]
	global_store_dwordx4 v[64:65], v[48:51], off
	global_store_dwordx4 v[64:65], v[52:55], off offset:64
	global_store_dwordx4 v[64:65], v[56:59], off offset:512
	global_store_dwordx4 v[64:65], v[60:63], off offset:576
	global_load_dword v48, v[176:177], off sc1
	s_waitcnt vmcnt(0)
	v_fmamk_f32 v48, v48, 0x3a800000, v205
	v_mul_f32_e32 v49, 0x4b800000, v48
	v_cmp_gt_f32_e32 vcc, s52, v48
	s_nop 1
	v_cndmask_b32_e32 v48, v48, v49, vcc
	v_rsq_f32_e32 v50, v48
	v_lshl_add_u64 v[48:49], v[146:147], 2, s[30:31]
	v_lshl_add_u64 v[48:49], v[48:49], 0, v[140:141]
	v_mul_f32_e32 v51, 0x45800000, v50
	v_cndmask_b32_e32 v50, v50, v51, vcc
	v_pk_mul_f32 v[44:45], v[44:45], v[50:51] op_sel_hi:[1,0]
	v_pk_mul_f32 v[46:47], v[46:47], v[50:51] op_sel_hi:[1,0]
	v_pk_mul_f32 v[40:41], v[40:41], v[50:51] op_sel_hi:[1,0]
	v_pk_mul_f32 v[42:43], v[42:43], v[50:51] op_sel_hi:[1,0]
	v_pk_mul_f32 v[52:53], v[36:37], v[50:51] op_sel_hi:[1,0]
	v_pk_mul_f32 v[54:55], v[38:39], v[50:51] op_sel_hi:[1,0]
	v_pk_mul_f32 v[56:57], v[32:33], v[50:51] op_sel_hi:[1,0]
	v_pk_mul_f32 v[50:51], v[34:35], v[50:51] op_sel_hi:[1,0]
	v_pk_mul_f32 v[34:35], v[14:15], v[46:47]
	v_pk_mul_f32 v[32:33], v[12:13], v[44:45]
	v_pk_mul_f32 v[38:39], v[10:11], v[42:43]
	v_pk_mul_f32 v[36:37], v[8:9], v[40:41]
	v_pk_mul_f32 v[42:43], v[6:7], v[54:55]
	v_pk_mul_f32 v[40:41], v[4:5], v[52:53]
	v_pk_mul_f32 v[46:47], v[2:3], v[50:51]
	v_pk_mul_f32 v[44:45], v[0:1], v[56:57]
	global_store_dwordx4 v[48:49], v[32:35], off
	global_store_dwordx4 v[48:49], v[36:39], off offset:64
	global_store_dwordx4 v[48:49], v[40:43], off offset:512
	global_store_dwordx4 v[48:49], v[44:47], off offset:576
	global_load_dword v32, v[178:179], off sc1
	s_waitcnt vmcnt(0)
	v_fmamk_f32 v32, v32, 0x3a800000, v205
	v_mul_f32_e32 v33, 0x4b800000, v32
	v_cmp_gt_f32_e32 vcc, s52, v32
	s_nop 1
	v_cndmask_b32_e32 v32, v32, v33, vcc
	v_rsq_f32_e32 v34, v32
	v_lshl_add_u64 v[32:33], v[144:145], 2, s[30:31]
	v_lshl_add_u64 v[40:41], v[32:33], 0, v[140:141]
	v_mul_f32_e32 v32, 0x45800000, v34
	v_cndmask_b32_e32 v32, v34, v32, vcc
	v_pk_mul_f32 v[28:29], v[28:29], v[32:33] op_sel_hi:[1,0]
	v_pk_mul_f32 v[30:31], v[30:31], v[32:33] op_sel_hi:[1,0]
	v_pk_mul_f32 v[34:35], v[24:25], v[32:33] op_sel_hi:[1,0]
	v_pk_mul_f32 v[36:37], v[26:27], v[32:33] op_sel_hi:[1,0]
	v_pk_mul_f32 v[38:39], v[164:165], v[32:33] op_sel_hi:[1,0]
	v_pk_mul_f32 v[42:43], v[160:161], v[32:33] op_sel_hi:[1,0]
	v_pk_mul_f32 v[44:45], v[168:169], v[32:33] op_sel_hi:[1,0]
	v_pk_mul_f32 v[46:47], v[166:167], v[32:33] op_sel_hi:[1,0]
	v_pk_mul_f32 v[26:27], v[14:15], v[30:31]
	v_pk_mul_f32 v[24:25], v[12:13], v[28:29]
	v_pk_mul_f32 v[30:31], v[10:11], v[36:37]
	v_pk_mul_f32 v[28:29], v[8:9], v[34:35]
	v_pk_mul_f32 v[34:35], v[6:7], v[42:43]
	v_pk_mul_f32 v[32:33], v[4:5], v[38:39]
	v_pk_mul_f32 v[38:39], v[2:3], v[46:47]
	v_pk_mul_f32 v[36:37], v[0:1], v[44:45]
	global_store_dwordx4 v[40:41], v[24:27], off
	global_store_dwordx4 v[40:41], v[28:31], off offset:64
	global_store_dwordx4 v[40:41], v[32:35], off offset:512
	global_store_dwordx4 v[40:41], v[36:39], off offset:576
	global_load_dword v24, v[180:181], off sc1
	s_and_b64 vcc, exec, s[6:7]
	s_mov_b64 s[6:7], -1
	s_waitcnt vmcnt(0)
	v_fmamk_f32 v24, v24, 0x3a800000, v205
	v_mul_f32_e32 v25, 0x4b800000, v24
	v_cmp_gt_f32_e64 s[8:9], s52, v24
	s_nop 1
	v_cndmask_b32_e64 v24, v24, v25, s[8:9]
	v_rsq_f32_e32 v26, v24
	v_lshl_add_u64 v[24:25], v[142:143], 2, s[30:31]
	v_lshl_add_u64 v[24:25], v[24:25], 0, v[140:141]
	v_mul_f32_e32 v27, 0x45800000, v26
	v_cndmask_b32_e64 v26, v26, v27, s[8:9]
	v_pk_mul_f32 v[18:19], v[18:19], v[26:27] op_sel_hi:[1,0]
	v_pk_mul_f32 v[16:17], v[16:17], v[26:27] op_sel_hi:[1,0]
	v_pk_mul_f32 v[22:23], v[22:23], v[26:27] op_sel_hi:[1,0]
	v_pk_mul_f32 v[20:21], v[20:21], v[26:27] op_sel_hi:[1,0]
	v_pk_mul_f32 v[28:29], v[162:163], v[26:27] op_sel_hi:[1,0]
	v_pk_mul_f32 v[30:31], v[158:159], v[26:27] op_sel_hi:[1,0]
	v_pk_mul_f32 v[32:33], v[172:173], v[26:27] op_sel_hi:[1,0]
	v_pk_mul_f32 v[26:27], v[170:171], v[26:27] op_sel_hi:[1,0]
	v_pk_mul_f32 v[14:15], v[14:15], v[16:17]
	v_pk_mul_f32 v[12:13], v[12:13], v[18:19]
	v_pk_mul_f32 v[10:11], v[10:11], v[20:21]
	v_pk_mul_f32 v[8:9], v[8:9], v[22:23]
	v_pk_mul_f32 v[6:7], v[6:7], v[30:31]
	v_pk_mul_f32 v[4:5], v[4:5], v[28:29]
	v_pk_mul_f32 v[2:3], v[2:3], v[26:27]
	v_pk_mul_f32 v[0:1], v[0:1], v[32:33]
	global_store_dwordx4 v[24:25], v[12:15], off
	global_store_dwordx4 v[24:25], v[8:11], off offset:64
	global_store_dwordx4 v[24:25], v[4:7], off offset:512
	global_store_dwordx4 v[24:25], v[0:3], off offset:576
	s_cbranch_vccnz .LBB0_1168
	s_andn2_b64 vcc, exec, s[12:13]
	s_cbranch_vccnz .LBB0_1167
	s_barrier
	s_branch .LBB0_1167
